# v83 + P13->P14 barrier split: XCD-local flag barrier plus a converter-done counter for the down-projection weights (8 local barriers)
# baseline (speedup 1.0000x reference)
.LBB0_1935:
	s_mov_b64 s[8:9], s[0:1]
	s_getreg_b32 s10, hwreg(HW_REG_XCC_ID, 0, 4)
	s_waitcnt vmcnt(0)
	s_barrier
	s_and_saveexec_b64 s[6:7], s[44:45]
	s_cbranch_execz .LBB0_1987
	s_cmp_eq_u32 s99, 0
	s_cbranch_scc1 .Lfb_skip_7
	s_load_dwordx2 s[8:9], s[0:1], 0x80
	s_and_b32 s10, s2, 7
	s_lshl_b32 s10, s10, 8
	s_add_i32 s10, s10, 0x1000
	s_lshr_b32 s11, s2, 3
	s_lshl_b32 s11, s11, 2
	v_mov_b32_e32 v1, s11
	v_mov_b32_e32 v0, 8
	s_mov_b32 s13, 0
	s_mov_b64 s[16:17], exec
	s_waitcnt lgkmcnt(0)
	s_add_u32 s18, s8, 0x3200
	s_addc_u32 s19, s9, 0
	s_add_u32 s8, s8, s10
	s_addc_u32 s9, s9, 0
	s_cmp_lt_u32 s2, 0x80
	s_cbranch_scc1 .Lb11_nocvt
	buffer_wbl2 sc1
	s_waitcnt vmcnt(0)
	v_mov_b32_e32 v6, 1
	v_mov_b32_e32 v7, 0
	global_atomic_add v7, v6, s[18:19]
	s_waitcnt vmcnt(0)
.Lb11_nocvt:
	global_store_dword v1, v0, s[8:9]
	buffer_inv sc1
	s_mov_b64 exec, 0xffffffff
	v_mbcnt_lo_u32_b32 v4, -1, 0
	v_lshlrev_b32_e32 v4, 2, v4
	v_mov_b32_e32 v0, 8

.Lfb_done_7:
	s_mov_b64 exec, s[16:17]
	v_mov_b32_e32 v7, 0
.Lb11_wpoll:
	global_load_dword v6, v7, s[18:19] sc1
	s_waitcnt vmcnt(0)
	v_cmp_gt_u32_e32 vcc, 0x80, v6
	s_and_b64 vcc, exec, vcc
	s_cbranch_vccz .Lb11_wdone
	s_sleep 1
	s_add_i32 s13, s13, 1
	s_cmp_lt_u32 s13, 0x8000
	s_cbranch_scc1 .Lb11_wpoll
